# waitcnt placement: removed the full vmcnt(0) store drain in the six GEMM unit preheaders (counted waits stay conservative)
# speedup vs baseline: 1.0030x; 1.0030x over previous
.LBB0_204:
	s_ashr_i32 s27, s26, 31
	s_lshl_b64 s[16:17], s[26:27], 20
	s_add_u32 s38, s0, s16
	s_addc_u32 s39, s1, s17
	s_and_b64 s[16:17], s[36:37], exec
	s_cselect_b32 s27, s39, s43
	s_cselect_b32 s73, s38, s42
	s_ashr_i32 s23, s22, 31
	s_lshl_b64 s[16:17], s[22:23], 20
	v_readlane_b32 s23, v255, 4
	s_add_u32 s40, s23, s16
	v_readlane_b32 s16, v255, 5
	s_addc_u32 s41, s16, s17
	s_and_b64 s[16:17], s[36:37], exec
	s_cselect_b32 s23, s41, s29
	s_cselect_b32 s74, s40, s28
	s_add_u32 s42, s42, 0x80080
	s_addc_u32 s43, s43, 0
	s_add_u32 s77, s28, 0x100
	v_mov_b32_e32 v4, 0
	s_addc_u32 s78, s29, 0
	s_mov_b32 s88, -2
	v_mov_b32_e32 v5, v4
	v_mov_b32_e32 v6, v4
	v_mov_b32_e32 v7, v4
	v_mov_b32_e32 v8, v4
	v_mov_b32_e32 v9, v4
	v_mov_b32_e32 v10, v4
	v_mov_b32_e32 v11, v4
	v_mov_b32_e32 v20, v4
	v_mov_b32_e32 v21, v4
	s_waitcnt lgkmcnt(0)
	v_mov_b32_e32 v22, v4
	v_mov_b32_e32 v23, v4
	v_mov_b32_e32 v24, v4
	v_mov_b32_e32 v25, v4
	v_mov_b32_e32 v26, v4
	v_mov_b32_e32 v27, v4
	v_mov_b32_e32 v36, v4
	v_mov_b32_e32 v37, v4
	v_mov_b32_e32 v38, v4
	v_mov_b32_e32 v39, v4
	v_mov_b32_e32 v40, v4
	v_mov_b32_e32 v41, v4
	v_mov_b32_e32 v42, v4
	v_mov_b32_e32 v43, v4
	v_mov_b32_e32 v52, v4
	v_mov_b32_e32 v53, v4
	v_mov_b32_e32 v54, v4
	v_mov_b32_e32 v55, v4
	v_mov_b32_e32 v56, v4
	v_mov_b32_e32 v57, v4
	v_mov_b32_e32 v58, v4
	v_mov_b32_e32 v59, v4
	v_mov_b32_e32 v12, v4
	v_mov_b32_e32 v13, v4
	v_mov_b32_e32 v14, v4
	v_mov_b32_e32 v15, v4
	v_mov_b32_e32 v16, v4
	v_mov_b32_e32 v17, v4
	v_mov_b32_e32 v18, v4
	v_mov_b32_e32 v19, v4
	v_mov_b32_e32 v28, v4
	v_mov_b32_e32 v29, v4
	v_mov_b32_e32 v30, v4
	v_mov_b32_e32 v31, v4
	v_mov_b32_e32 v32, v4
	v_mov_b32_e32 v33, v4
	v_mov_b32_e32 v34, v4
	v_mov_b32_e32 v35, v4
	v_mov_b32_e32 v44, v4
	v_mov_b32_e32 v45, v4
	v_mov_b32_e32 v46, v4
	v_mov_b32_e32 v47, v4
	v_mov_b32_e32 v48, v4
	v_mov_b32_e32 v49, v4
	v_mov_b32_e32 v50, v4
	v_mov_b32_e32 v51, v4
	v_mov_b32_e32 v60, v4
	v_mov_b32_e32 v61, v4
	v_mov_b32_e32 v62, v4
	v_mov_b32_e32 v63, v4
	v_mov_b32_e32 v64, v4
	v_mov_b32_e32 v65, v4
	v_mov_b32_e32 v66, v4
	v_mov_b32_e32 v67, v4
	v_mov_b32_e32 v68, v4
	v_mov_b32_e32 v69, v4
	v_mov_b32_e32 v70, v4
	v_mov_b32_e32 v71, v4
	v_mov_b32_e32 v72, v4
	v_mov_b32_e32 v73, v4
	v_mov_b32_e32 v74, v4
	v_mov_b32_e32 v75, v4
	v_mov_b32_e32 v84, v4
	v_mov_b32_e32 v85, v4
	v_mov_b32_e32 v86, v4
	v_mov_b32_e32 v87, v4
	v_mov_b32_e32 v88, v4
	v_mov_b32_e32 v89, v4
	v_mov_b32_e32 v90, v4
	v_mov_b32_e32 v91, v4
	v_mov_b32_e32 v100, v4
	v_mov_b32_e32 v101, v4
	v_mov_b32_e32 v102, v4
	v_mov_b32_e32 v103, v4
	v_mov_b32_e32 v104, v4
	v_mov_b32_e32 v105, v4
	v_mov_b32_e32 v106, v4
	v_mov_b32_e32 v107, v4
	v_mov_b32_e32 v116, v4
	v_mov_b32_e32 v117, v4
	v_mov_b32_e32 v118, v4
	v_mov_b32_e32 v119, v4
	v_mov_b32_e32 v120, v4
	v_mov_b32_e32 v121, v4
	v_mov_b32_e32 v122, v4
	v_mov_b32_e32 v123, v4
	v_mov_b32_e32 v76, v4
	v_mov_b32_e32 v77, v4
	v_mov_b32_e32 v78, v4
	v_mov_b32_e32 v79, v4
	v_mov_b32_e32 v80, v4
	v_mov_b32_e32 v81, v4
	v_mov_b32_e32 v82, v4
	v_mov_b32_e32 v83, v4
	v_mov_b32_e32 v92, v4
	v_mov_b32_e32 v93, v4
	v_mov_b32_e32 v94, v4
	v_mov_b32_e32 v95, v4
	v_mov_b32_e32 v96, v4
	v_mov_b32_e32 v97, v4
	v_mov_b32_e32 v98, v4
	v_mov_b32_e32 v99, v4
	v_mov_b32_e32 v108, v4
	v_mov_b32_e32 v109, v4
	v_mov_b32_e32 v110, v4
	v_mov_b32_e32 v111, v4
	v_mov_b32_e32 v112, v4
	v_mov_b32_e32 v113, v4
	v_mov_b32_e32 v114, v4
	v_mov_b32_e32 v115, v4
	v_mov_b32_e32 v124, v4
	v_mov_b32_e32 v125, v4
	v_mov_b32_e32 v126, v4
	v_mov_b32_e32 v127, v4
	v_mov_b32_e32 v128, v4
	v_mov_b32_e32 v129, v4
	v_mov_b32_e32 v130, v4
	v_mov_b32_e32 v131, v4

.LBB0_365:
	s_add_u32 s31, s28, 0x100
	v_mov_b32_e32 v4, 0
	s_addc_u32 s33, s29, 0
	s_mov_b32 s22, -2
	v_mov_b32_e32 v5, v4
	v_mov_b32_e32 v6, v4
	v_mov_b32_e32 v7, v4
	v_mov_b32_e32 v8, v4
	v_mov_b32_e32 v9, v4
	v_mov_b32_e32 v10, v4
	v_mov_b32_e32 v11, v4
	v_mov_b32_e32 v20, v4
	v_mov_b32_e32 v21, v4
	v_mov_b32_e32 v22, v4
	v_mov_b32_e32 v23, v4
	v_mov_b32_e32 v24, v4
	v_mov_b32_e32 v25, v4
	s_waitcnt lgkmcnt(0)
	v_mov_b32_e32 v26, v4
	v_mov_b32_e32 v27, v4
	v_mov_b32_e32 v36, v4
	v_mov_b32_e32 v37, v4
	v_mov_b32_e32 v38, v4
	v_mov_b32_e32 v39, v4
	v_mov_b32_e32 v40, v4
	v_mov_b32_e32 v41, v4
	v_mov_b32_e32 v42, v4
	v_mov_b32_e32 v43, v4
	v_mov_b32_e32 v52, v4
	v_mov_b32_e32 v53, v4
	v_mov_b32_e32 v54, v4
	v_mov_b32_e32 v55, v4
	v_mov_b32_e32 v56, v4
	v_mov_b32_e32 v57, v4
	v_mov_b32_e32 v58, v4
	v_mov_b32_e32 v59, v4
	v_mov_b32_e32 v12, v4
	v_mov_b32_e32 v13, v4
	v_mov_b32_e32 v14, v4
	v_mov_b32_e32 v15, v4
	v_mov_b32_e32 v16, v4
	v_mov_b32_e32 v17, v4
	v_mov_b32_e32 v18, v4
	v_mov_b32_e32 v19, v4
	v_mov_b32_e32 v28, v4
	v_mov_b32_e32 v29, v4
	v_mov_b32_e32 v30, v4
	v_mov_b32_e32 v31, v4
	v_mov_b32_e32 v32, v4
	v_mov_b32_e32 v33, v4
	v_mov_b32_e32 v34, v4
	v_mov_b32_e32 v35, v4
	v_mov_b32_e32 v44, v4
	v_mov_b32_e32 v45, v4
	v_mov_b32_e32 v46, v4
	v_mov_b32_e32 v47, v4
	v_mov_b32_e32 v48, v4
	v_mov_b32_e32 v49, v4
	v_mov_b32_e32 v50, v4
	v_mov_b32_e32 v51, v4
	v_mov_b32_e32 v60, v4
	v_mov_b32_e32 v61, v4
	v_mov_b32_e32 v62, v4
	v_mov_b32_e32 v63, v4
	v_mov_b32_e32 v64, v4
	v_mov_b32_e32 v65, v4
	v_mov_b32_e32 v66, v4
	v_mov_b32_e32 v67, v4
	v_mov_b32_e32 v68, v4
	v_mov_b32_e32 v69, v4
	v_mov_b32_e32 v70, v4
	v_mov_b32_e32 v71, v4
	v_mov_b32_e32 v72, v4
	v_mov_b32_e32 v73, v4
	v_mov_b32_e32 v74, v4
	v_mov_b32_e32 v75, v4
	v_mov_b32_e32 v84, v4
	v_mov_b32_e32 v85, v4
	v_mov_b32_e32 v86, v4
	v_mov_b32_e32 v87, v4
	v_mov_b32_e32 v88, v4
	v_mov_b32_e32 v89, v4
	v_mov_b32_e32 v90, v4
	v_mov_b32_e32 v91, v4
	v_mov_b32_e32 v100, v4
	v_mov_b32_e32 v101, v4
	v_mov_b32_e32 v102, v4
	v_mov_b32_e32 v103, v4
	v_mov_b32_e32 v104, v4
	v_mov_b32_e32 v105, v4
	v_mov_b32_e32 v106, v4
	v_mov_b32_e32 v107, v4
	v_mov_b32_e32 v116, v4
	v_mov_b32_e32 v117, v4
	v_mov_b32_e32 v118, v4
	v_mov_b32_e32 v119, v4
	v_mov_b32_e32 v120, v4
	v_mov_b32_e32 v121, v4
	v_mov_b32_e32 v122, v4
	v_mov_b32_e32 v123, v4
	v_mov_b32_e32 v76, v4
	v_mov_b32_e32 v77, v4
	v_mov_b32_e32 v78, v4
	v_mov_b32_e32 v79, v4
	v_mov_b32_e32 v80, v4
	v_mov_b32_e32 v81, v4
	v_mov_b32_e32 v82, v4
	v_mov_b32_e32 v83, v4
	v_mov_b32_e32 v92, v4
	v_mov_b32_e32 v93, v4
	v_mov_b32_e32 v94, v4
	v_mov_b32_e32 v95, v4
	v_mov_b32_e32 v96, v4
	v_mov_b32_e32 v97, v4
	v_mov_b32_e32 v98, v4
	v_mov_b32_e32 v99, v4
	v_mov_b32_e32 v108, v4
	v_mov_b32_e32 v109, v4
	v_mov_b32_e32 v110, v4
	v_mov_b32_e32 v111, v4
	v_mov_b32_e32 v112, v4
	v_mov_b32_e32 v113, v4
	v_mov_b32_e32 v114, v4
	v_mov_b32_e32 v115, v4
	v_mov_b32_e32 v124, v4
	v_mov_b32_e32 v125, v4
	v_mov_b32_e32 v126, v4
	v_mov_b32_e32 v127, v4
	v_mov_b32_e32 v128, v4
	v_mov_b32_e32 v129, v4
	v_mov_b32_e32 v130, v4
	v_mov_b32_e32 v131, v4

.LBB0_445:
	s_ashr_i32 s37, s36, 31
	s_lshl_b64 s[16:17], s[36:37], 20
	s_add_u32 s40, s0, s16
	s_addc_u32 s41, s1, s17
	s_and_b64 s[16:17], s[38:39], exec
	s_cselect_b32 s37, s41, s45
	s_cselect_b32 s88, s40, s44
	s_ashr_i32 s27, s26, 31
	s_lshl_b64 s[16:17], s[26:27], 20
	s_add_u32 s42, s3, s16
	s_addc_u32 s43, s31, s17
	s_and_b64 s[16:17], s[38:39], exec
	s_cselect_b32 s27, s43, s29
	s_cselect_b32 s89, s42, s28
	s_add_u32 s44, s44, 0x80080
	s_addc_u32 s45, s45, 0
	s_add_u32 s91, s28, 0x100
	v_mov_b32_e32 v4, 0
	v_mov_b32_e32 v235, 0x42000000
	v_mov_b32_e32 v233, 0x400
	v_mov_b64_e32 v[240:241], 0x1080
	s_addc_u32 s96, s29, 0
	s_mov_b32 vcc_lo, -2
	v_mov_b32_e32 v5, v4
	v_mov_b32_e32 v6, v4
	v_mov_b32_e32 v7, v4
	v_mov_b32_e32 v8, v4
	v_mov_b32_e32 v9, v4
	v_mov_b32_e32 v10, v4
	v_mov_b32_e32 v11, v4
	v_mov_b32_e32 v20, v4
	v_mov_b32_e32 v21, v4
	v_mov_b32_e32 v22, v4
	v_mov_b32_e32 v23, v4
	v_mov_b32_e32 v24, v4
	v_mov_b32_e32 v25, v4
	s_waitcnt lgkmcnt(0)
	v_mov_b32_e32 v26, v4
	v_mov_b32_e32 v27, v4
	v_mov_b32_e32 v36, v4
	v_mov_b32_e32 v37, v4
	v_mov_b32_e32 v38, v4
	v_mov_b32_e32 v39, v4
	v_mov_b32_e32 v40, v4
	v_mov_b32_e32 v41, v4
	v_mov_b32_e32 v42, v4
	v_mov_b32_e32 v43, v4
	v_mov_b32_e32 v52, v4
	v_mov_b32_e32 v53, v4
	v_mov_b32_e32 v54, v4
	v_mov_b32_e32 v55, v4
	v_mov_b32_e32 v56, v4
	v_mov_b32_e32 v57, v4
	v_mov_b32_e32 v58, v4
	v_mov_b32_e32 v59, v4
	v_mov_b32_e32 v12, v4
	v_mov_b32_e32 v13, v4
	v_mov_b32_e32 v14, v4
	v_mov_b32_e32 v15, v4
	v_mov_b32_e32 v16, v4
	v_mov_b32_e32 v17, v4
	v_mov_b32_e32 v18, v4
	v_mov_b32_e32 v19, v4
	v_mov_b32_e32 v28, v4
	v_mov_b32_e32 v29, v4
	v_mov_b32_e32 v30, v4
	v_mov_b32_e32 v31, v4
	v_mov_b32_e32 v32, v4
	v_mov_b32_e32 v33, v4
	v_mov_b32_e32 v34, v4
	v_mov_b32_e32 v35, v4
	v_mov_b32_e32 v44, v4
	v_mov_b32_e32 v45, v4
	v_mov_b32_e32 v46, v4
	v_mov_b32_e32 v47, v4
	v_mov_b32_e32 v48, v4
	v_mov_b32_e32 v49, v4
	v_mov_b32_e32 v50, v4
	v_mov_b32_e32 v51, v4
	v_mov_b32_e32 v60, v4
	v_mov_b32_e32 v61, v4
	v_mov_b32_e32 v62, v4
	v_mov_b32_e32 v63, v4
	v_mov_b32_e32 v64, v4
	v_mov_b32_e32 v65, v4
	v_mov_b32_e32 v66, v4
	v_mov_b32_e32 v67, v4
	v_mov_b32_e32 v68, v4
	v_mov_b32_e32 v69, v4
	v_mov_b32_e32 v70, v4
	v_mov_b32_e32 v71, v4
	v_mov_b32_e32 v72, v4
	v_mov_b32_e32 v73, v4
	v_mov_b32_e32 v74, v4
	v_mov_b32_e32 v75, v4
	v_mov_b32_e32 v84, v4
	v_mov_b32_e32 v85, v4
	v_mov_b32_e32 v86, v4
	v_mov_b32_e32 v87, v4
	v_mov_b32_e32 v88, v4
	v_mov_b32_e32 v89, v4
	v_mov_b32_e32 v90, v4
	v_mov_b32_e32 v91, v4
	v_mov_b32_e32 v100, v4
	v_mov_b32_e32 v101, v4
	v_mov_b32_e32 v102, v4
	v_mov_b32_e32 v103, v4
	v_mov_b32_e32 v104, v4
	v_mov_b32_e32 v105, v4
	v_mov_b32_e32 v106, v4
	v_mov_b32_e32 v107, v4
	v_mov_b32_e32 v116, v4
	v_mov_b32_e32 v117, v4
	v_mov_b32_e32 v118, v4
	v_mov_b32_e32 v119, v4
	v_mov_b32_e32 v120, v4
	v_mov_b32_e32 v121, v4
	v_mov_b32_e32 v122, v4
	v_mov_b32_e32 v123, v4
	v_mov_b32_e32 v76, v4
	v_mov_b32_e32 v77, v4
	v_mov_b32_e32 v78, v4
	v_mov_b32_e32 v79, v4
	v_mov_b32_e32 v80, v4
	v_mov_b32_e32 v81, v4
	v_mov_b32_e32 v82, v4
	v_mov_b32_e32 v83, v4
	v_mov_b32_e32 v92, v4
	v_mov_b32_e32 v93, v4
	v_mov_b32_e32 v94, v4
	v_mov_b32_e32 v95, v4
	v_mov_b32_e32 v96, v4
	v_mov_b32_e32 v97, v4
	v_mov_b32_e32 v98, v4
	v_mov_b32_e32 v99, v4
	v_mov_b32_e32 v108, v4
	v_mov_b32_e32 v109, v4
	v_mov_b32_e32 v110, v4
	v_mov_b32_e32 v111, v4
	v_mov_b32_e32 v112, v4
	v_mov_b32_e32 v113, v4
	v_mov_b32_e32 v114, v4
	v_mov_b32_e32 v115, v4
	v_mov_b32_e32 v124, v4
	v_mov_b32_e32 v125, v4
	v_mov_b32_e32 v126, v4
	v_mov_b32_e32 v127, v4
	v_mov_b32_e32 v128, v4
	v_mov_b32_e32 v129, v4
	v_mov_b32_e32 v130, v4
	v_mov_b32_e32 v131, v4

.LBB0_789:
	s_ashr_i32 s19, s18, 31
	s_lshl_b64 s[10:11], s[18:19], 20
	v_readlane_b32 s16, v252, 15
	s_add_u32 s50, s16, s10
	v_readlane_b32 s10, v252, 16
	s_addc_u32 s51, s10, s11
	s_and_b64 s[10:11], s[46:47], exec
	s_cselect_b32 s19, s51, s73
	s_cselect_b32 s31, s50, s72
	s_ashr_i32 s23, s22, 31
	s_lshl_b64 s[10:11], s[22:23], 20
	s_add_u32 s26, s36, s10
	s_addc_u32 s27, s37, s11
	s_and_b64 s[10:11], s[46:47], exec
	s_cselect_b32 s23, s27, s29
	s_cselect_b32 s33, s26, s28
	s_add_u32 vcc_lo, s72, 0x80080
	s_addc_u32 vcc_hi, s73, 0
	s_add_u32 s48, s28, 0x100
	v_mov_b32_e32 v4, 0
	s_addc_u32 s49, s29, 0
	s_mov_b32 s10, -2
	v_mov_b32_e32 v5, v4
	v_mov_b32_e32 v6, v4
	v_mov_b32_e32 v7, v4
	v_mov_b32_e32 v8, v4
	v_mov_b32_e32 v9, v4
	v_mov_b32_e32 v10, v4
	v_mov_b32_e32 v11, v4
	v_mov_b32_e32 v20, v4
	v_mov_b32_e32 v21, v4
	v_mov_b32_e32 v22, v4
	v_mov_b32_e32 v23, v4
	v_mov_b32_e32 v24, v4
	v_mov_b32_e32 v25, v4
	s_waitcnt lgkmcnt(0)
	v_mov_b32_e32 v26, v4
	v_mov_b32_e32 v27, v4
	v_mov_b32_e32 v36, v4
	v_mov_b32_e32 v37, v4
	v_mov_b32_e32 v38, v4
	v_mov_b32_e32 v39, v4
	v_mov_b32_e32 v40, v4
	v_mov_b32_e32 v41, v4
	v_mov_b32_e32 v42, v4
	v_mov_b32_e32 v43, v4
	v_mov_b32_e32 v52, v4
	v_mov_b32_e32 v53, v4
	v_mov_b32_e32 v54, v4
	v_mov_b32_e32 v55, v4
	v_mov_b32_e32 v56, v4
	v_mov_b32_e32 v57, v4
	v_mov_b32_e32 v58, v4
	v_mov_b32_e32 v59, v4
	v_mov_b32_e32 v12, v4
	v_mov_b32_e32 v13, v4
	v_mov_b32_e32 v14, v4
	v_mov_b32_e32 v15, v4
	v_mov_b32_e32 v16, v4
	v_mov_b32_e32 v17, v4
	v_mov_b32_e32 v18, v4
	v_mov_b32_e32 v19, v4
	v_mov_b32_e32 v28, v4
	v_mov_b32_e32 v29, v4
	v_mov_b32_e32 v30, v4
	v_mov_b32_e32 v31, v4
	v_mov_b32_e32 v32, v4
	v_mov_b32_e32 v33, v4
	v_mov_b32_e32 v34, v4
	v_mov_b32_e32 v35, v4
	v_mov_b32_e32 v44, v4
	v_mov_b32_e32 v45, v4
	v_mov_b32_e32 v46, v4
	v_mov_b32_e32 v47, v4
	v_mov_b32_e32 v48, v4
	v_mov_b32_e32 v49, v4
	v_mov_b32_e32 v50, v4
	v_mov_b32_e32 v51, v4
	v_mov_b32_e32 v60, v4
	v_mov_b32_e32 v61, v4
	v_mov_b32_e32 v62, v4
	v_mov_b32_e32 v63, v4
	v_mov_b32_e32 v64, v4
	v_mov_b32_e32 v65, v4
	v_mov_b32_e32 v66, v4
	v_mov_b32_e32 v67, v4
	v_mov_b32_e32 v68, v4
	v_mov_b32_e32 v69, v4
	v_mov_b32_e32 v70, v4
	v_mov_b32_e32 v71, v4
	v_mov_b32_e32 v72, v4
	v_mov_b32_e32 v73, v4
	v_mov_b32_e32 v74, v4
	v_mov_b32_e32 v75, v4
	v_mov_b32_e32 v84, v4
	v_mov_b32_e32 v85, v4
	v_mov_b32_e32 v86, v4
	v_mov_b32_e32 v87, v4
	v_mov_b32_e32 v88, v4
	v_mov_b32_e32 v89, v4
	v_mov_b32_e32 v90, v4
	v_mov_b32_e32 v91, v4
	v_mov_b32_e32 v100, v4
	v_mov_b32_e32 v101, v4
	v_mov_b32_e32 v102, v4
	v_mov_b32_e32 v103, v4
	v_mov_b32_e32 v104, v4
	v_mov_b32_e32 v105, v4
	v_mov_b32_e32 v106, v4
	v_mov_b32_e32 v107, v4
	v_mov_b32_e32 v116, v4
	v_mov_b32_e32 v117, v4
	v_mov_b32_e32 v118, v4
	v_mov_b32_e32 v119, v4
	v_mov_b32_e32 v120, v4
	v_mov_b32_e32 v121, v4
	v_mov_b32_e32 v122, v4
	v_mov_b32_e32 v123, v4
	v_mov_b32_e32 v76, v4
	v_mov_b32_e32 v77, v4
	v_mov_b32_e32 v78, v4
	v_mov_b32_e32 v79, v4
	v_mov_b32_e32 v80, v4
	v_mov_b32_e32 v81, v4
	v_mov_b32_e32 v82, v4
	v_mov_b32_e32 v83, v4
	v_mov_b32_e32 v92, v4
	v_mov_b32_e32 v93, v4
	v_mov_b32_e32 v94, v4
	v_mov_b32_e32 v95, v4
	v_mov_b32_e32 v96, v4
	v_mov_b32_e32 v97, v4
	v_mov_b32_e32 v98, v4
	v_mov_b32_e32 v99, v4
	v_mov_b32_e32 v108, v4
	v_mov_b32_e32 v109, v4
	v_mov_b32_e32 v110, v4
	v_mov_b32_e32 v111, v4
	v_mov_b32_e32 v112, v4
	v_mov_b32_e32 v113, v4
	v_mov_b32_e32 v114, v4
	v_mov_b32_e32 v115, v4
	v_mov_b32_e32 v124, v4
	v_mov_b32_e32 v125, v4
	v_mov_b32_e32 v126, v4
	v_mov_b32_e32 v127, v4
	v_mov_b32_e32 v128, v4
	v_mov_b32_e32 v129, v4
	v_mov_b32_e32 v130, v4
	v_mov_b32_e32 v131, v4

.LBB0_869:
	s_ashr_i32 s37, s36, 31
	s_lshl_b64 s[16:17], s[36:37], 20
	s_add_u32 s40, s0, s16
	s_addc_u32 s41, s1, s17
	s_and_b64 s[16:17], s[38:39], exec
	s_cselect_b32 s37, s41, s45
	s_cselect_b32 s88, s40, s44
	s_ashr_i32 s27, s26, 31
	s_lshl_b64 s[16:17], s[26:27], 20
	s_add_u32 s42, s3, s16
	s_addc_u32 s43, s31, s17
	s_and_b64 s[16:17], s[38:39], exec
	s_cselect_b32 s27, s43, s29
	s_cselect_b32 s89, s42, s28
	s_add_u32 s44, s44, 0x80080
	s_addc_u32 s45, s45, 0
	s_add_u32 s91, s28, 0x100
	v_mov_b32_e32 v4, 0
	s_addc_u32 s96, s29, 0
	s_mov_b32 vcc_lo, -2
	v_mov_b32_e32 v5, v4
	v_mov_b32_e32 v6, v4
	v_mov_b32_e32 v7, v4
	v_mov_b32_e32 v8, v4
	v_mov_b32_e32 v9, v4
	v_mov_b32_e32 v10, v4
	v_mov_b32_e32 v11, v4
	v_mov_b32_e32 v20, v4
	v_mov_b32_e32 v21, v4
	v_mov_b32_e32 v22, v4
	v_mov_b32_e32 v23, v4
	v_mov_b32_e32 v24, v4
	v_mov_b32_e32 v25, v4
	s_waitcnt lgkmcnt(0)
	v_mov_b32_e32 v26, v4
	v_mov_b32_e32 v27, v4
	v_mov_b32_e32 v36, v4
	v_mov_b32_e32 v37, v4
	v_mov_b32_e32 v38, v4
	v_mov_b32_e32 v39, v4
	v_mov_b32_e32 v40, v4
	v_mov_b32_e32 v41, v4
	v_mov_b32_e32 v42, v4
	v_mov_b32_e32 v43, v4
	v_mov_b32_e32 v52, v4
	v_mov_b32_e32 v53, v4
	v_mov_b32_e32 v54, v4
	v_mov_b32_e32 v55, v4
	v_mov_b32_e32 v56, v4
	v_mov_b32_e32 v57, v4
	v_mov_b32_e32 v58, v4
	v_mov_b32_e32 v59, v4
	v_mov_b32_e32 v12, v4
	v_mov_b32_e32 v13, v4
	v_mov_b32_e32 v14, v4
	v_mov_b32_e32 v15, v4
	v_mov_b32_e32 v16, v4
	v_mov_b32_e32 v17, v4
	v_mov_b32_e32 v18, v4
	v_mov_b32_e32 v19, v4
	v_mov_b32_e32 v28, v4
	v_mov_b32_e32 v29, v4
	v_mov_b32_e32 v30, v4
	v_mov_b32_e32 v31, v4
	v_mov_b32_e32 v32, v4
	v_mov_b32_e32 v33, v4
	v_mov_b32_e32 v34, v4
	v_mov_b32_e32 v35, v4
	v_mov_b32_e32 v44, v4
	v_mov_b32_e32 v45, v4
	v_mov_b32_e32 v46, v4
	v_mov_b32_e32 v47, v4
	v_mov_b32_e32 v48, v4
	v_mov_b32_e32 v49, v4
	v_mov_b32_e32 v50, v4
	v_mov_b32_e32 v51, v4
	v_mov_b32_e32 v60, v4
	v_mov_b32_e32 v61, v4
	v_mov_b32_e32 v62, v4
	v_mov_b32_e32 v63, v4
	v_mov_b32_e32 v64, v4
	v_mov_b32_e32 v65, v4
	v_mov_b32_e32 v66, v4
	v_mov_b32_e32 v67, v4
	v_mov_b32_e32 v68, v4
	v_mov_b32_e32 v69, v4
	v_mov_b32_e32 v70, v4
	v_mov_b32_e32 v71, v4
	v_mov_b32_e32 v72, v4
	v_mov_b32_e32 v73, v4
	v_mov_b32_e32 v74, v4
	v_mov_b32_e32 v75, v4
	v_mov_b32_e32 v84, v4
	v_mov_b32_e32 v85, v4
	v_mov_b32_e32 v86, v4
	v_mov_b32_e32 v87, v4
	v_mov_b32_e32 v88, v4
	v_mov_b32_e32 v89, v4
	v_mov_b32_e32 v90, v4
	v_mov_b32_e32 v91, v4
	v_mov_b32_e32 v100, v4
	v_mov_b32_e32 v101, v4
	v_mov_b32_e32 v102, v4
	v_mov_b32_e32 v103, v4
	v_mov_b32_e32 v104, v4
	v_mov_b32_e32 v105, v4
	v_mov_b32_e32 v106, v4
	v_mov_b32_e32 v107, v4
	v_mov_b32_e32 v116, v4
	v_mov_b32_e32 v117, v4
	v_mov_b32_e32 v118, v4
	v_mov_b32_e32 v119, v4
	v_mov_b32_e32 v120, v4
	v_mov_b32_e32 v121, v4
	v_mov_b32_e32 v122, v4
	v_mov_b32_e32 v123, v4
	v_mov_b32_e32 v76, v4
	v_mov_b32_e32 v77, v4
	v_mov_b32_e32 v78, v4
	v_mov_b32_e32 v79, v4
	v_mov_b32_e32 v80, v4
	v_mov_b32_e32 v81, v4
	v_mov_b32_e32 v82, v4
	v_mov_b32_e32 v83, v4
	v_mov_b32_e32 v92, v4
	v_mov_b32_e32 v93, v4
	v_mov_b32_e32 v94, v4
	v_mov_b32_e32 v95, v4
	v_mov_b32_e32 v96, v4
	v_mov_b32_e32 v97, v4
	v_mov_b32_e32 v98, v4
	v_mov_b32_e32 v99, v4
	v_mov_b32_e32 v108, v4
	v_mov_b32_e32 v109, v4
	v_mov_b32_e32 v110, v4
	v_mov_b32_e32 v111, v4
	v_mov_b32_e32 v112, v4
	v_mov_b32_e32 v113, v4
	v_mov_b32_e32 v114, v4
	v_mov_b32_e32 v115, v4
	v_mov_b32_e32 v124, v4
	v_mov_b32_e32 v125, v4
	v_mov_b32_e32 v126, v4
	v_mov_b32_e32 v127, v4
	v_mov_b32_e32 v128, v4
	v_mov_b32_e32 v129, v4
	v_mov_b32_e32 v130, v4
	v_mov_b32_e32 v131, v4

.LBB0_1034:
	s_add_u32 vcc_lo, s28, 0x100
	v_mov_b32_e32 v4, 0
	s_addc_u32 vcc_hi, s29, 0
	s_mov_b32 s48, -2
	v_mov_b32_e32 v5, v4
	v_mov_b32_e32 v6, v4
	v_mov_b32_e32 v7, v4
	v_mov_b32_e32 v8, v4
	v_mov_b32_e32 v9, v4
	v_mov_b32_e32 v10, v4
	v_mov_b32_e32 v11, v4
	v_mov_b32_e32 v20, v4
	v_mov_b32_e32 v21, v4
	v_mov_b32_e32 v22, v4
	v_mov_b32_e32 v23, v4
	v_mov_b32_e32 v24, v4
	v_mov_b32_e32 v25, v4
	s_waitcnt lgkmcnt(0)
	v_mov_b32_e32 v26, v4
	v_mov_b32_e32 v27, v4
	v_mov_b32_e32 v36, v4
	v_mov_b32_e32 v37, v4
	v_mov_b32_e32 v38, v4
	v_mov_b32_e32 v39, v4
	v_mov_b32_e32 v40, v4
	v_mov_b32_e32 v41, v4
	v_mov_b32_e32 v42, v4
	v_mov_b32_e32 v43, v4
	v_mov_b32_e32 v52, v4
	v_mov_b32_e32 v53, v4
	v_mov_b32_e32 v54, v4
	v_mov_b32_e32 v55, v4
	v_mov_b32_e32 v56, v4
	v_mov_b32_e32 v57, v4
	v_mov_b32_e32 v58, v4
	v_mov_b32_e32 v59, v4
	v_mov_b32_e32 v12, v4
	v_mov_b32_e32 v13, v4
	v_mov_b32_e32 v14, v4
	v_mov_b32_e32 v15, v4
	v_mov_b32_e32 v16, v4
	v_mov_b32_e32 v17, v4
	v_mov_b32_e32 v18, v4
	v_mov_b32_e32 v19, v4
	v_mov_b32_e32 v28, v4
	v_mov_b32_e32 v29, v4
	v_mov_b32_e32 v30, v4
	v_mov_b32_e32 v31, v4
	v_mov_b32_e32 v32, v4
	v_mov_b32_e32 v33, v4
	v_mov_b32_e32 v34, v4
	v_mov_b32_e32 v35, v4
	v_mov_b32_e32 v44, v4
	v_mov_b32_e32 v45, v4
	v_mov_b32_e32 v46, v4
	v_mov_b32_e32 v47, v4
	v_mov_b32_e32 v48, v4
	v_mov_b32_e32 v49, v4
	v_mov_b32_e32 v50, v4
	v_mov_b32_e32 v51, v4
	v_mov_b32_e32 v60, v4
	v_mov_b32_e32 v61, v4
	v_mov_b32_e32 v62, v4
	v_mov_b32_e32 v63, v4
	v_mov_b32_e32 v64, v4
	v_mov_b32_e32 v65, v4
	v_mov_b32_e32 v66, v4
	v_mov_b32_e32 v67, v4
	v_mov_b32_e32 v68, v4
	v_mov_b32_e32 v69, v4
	v_mov_b32_e32 v70, v4
	v_mov_b32_e32 v71, v4
	v_mov_b32_e32 v72, v4
	v_mov_b32_e32 v73, v4
	v_mov_b32_e32 v74, v4
	v_mov_b32_e32 v75, v4
	v_mov_b32_e32 v84, v4
	v_mov_b32_e32 v85, v4
	v_mov_b32_e32 v86, v4
	v_mov_b32_e32 v87, v4
	v_mov_b32_e32 v88, v4
	v_mov_b32_e32 v89, v4
	v_mov_b32_e32 v90, v4
	v_mov_b32_e32 v91, v4
	v_mov_b32_e32 v100, v4
	v_mov_b32_e32 v101, v4
	v_mov_b32_e32 v102, v4
	v_mov_b32_e32 v103, v4
	v_mov_b32_e32 v104, v4
	v_mov_b32_e32 v105, v4
	v_mov_b32_e32 v106, v4
	v_mov_b32_e32 v107, v4
	v_mov_b32_e32 v116, v4
	v_mov_b32_e32 v117, v4
	v_mov_b32_e32 v118, v4
	v_mov_b32_e32 v119, v4
	v_mov_b32_e32 v120, v4
	v_mov_b32_e32 v121, v4
	v_mov_b32_e32 v122, v4
	v_mov_b32_e32 v123, v4
	v_mov_b32_e32 v76, v4
	v_mov_b32_e32 v77, v4
	v_mov_b32_e32 v78, v4
	v_mov_b32_e32 v79, v4
	v_mov_b32_e32 v80, v4
	v_mov_b32_e32 v81, v4
	v_mov_b32_e32 v82, v4
	v_mov_b32_e32 v83, v4
	v_mov_b32_e32 v92, v4
	v_mov_b32_e32 v93, v4
	v_mov_b32_e32 v94, v4
	v_mov_b32_e32 v95, v4
	v_mov_b32_e32 v96, v4
	v_mov_b32_e32 v97, v4
	v_mov_b32_e32 v98, v4
	v_mov_b32_e32 v99, v4
	v_mov_b32_e32 v108, v4
	v_mov_b32_e32 v109, v4
	v_mov_b32_e32 v110, v4
	v_mov_b32_e32 v111, v4
	v_mov_b32_e32 v112, v4
	v_mov_b32_e32 v113, v4
	v_mov_b32_e32 v114, v4
	v_mov_b32_e32 v115, v4
	v_mov_b32_e32 v124, v4
	v_mov_b32_e32 v125, v4
	v_mov_b32_e32 v126, v4
	v_mov_b32_e32 v127, v4
	v_mov_b32_e32 v128, v4
	v_mov_b32_e32 v129, v4
	v_mov_b32_e32 v130, v4
	v_mov_b32_e32 v131, v4
